# 8 gemm_phase prologues: second LDS-DMA batch issued before the first wait (vmcnt(2)+barrier moved below it as vmcnt(8)) so both batches' memory latencies overlap
# speedup vs baseline: 1.0065x; 1.0058x over previous
; #define PG8_STAGE(bufoff, gbase, voff) do { _Pragma("unroll") for (int _i = 0; _i < 2; ++_i) \
;         __builtin_amdgcn_global_load_lds((const unsigned*)((const char*)(gbase) + (voff)[_i]), (LAS unsigned*)(lds + (bufoff) + ldsw + _i * 8192), 16, 0, 0); } while (0)
; #define PG8_WAIT_V(n) asm volatile("s_waitcnt vmcnt(" #n ")" ::: "memory")
; #define PG8_BAR __builtin_amdgcn_s_barrier()
; template <class Epi>
; __device__ __forceinline__ void gemm_phase(LAS unsigned char* lds, const Gemm g, const StaticOrder& S, const Epi& E) {
;     ...
;     const char* cA = (const char*)g.A + (size_t)cur.pm * tstepA; const char* cB = (const char*)g.Bt + (size_t)cur.pn * tstepB;
;     PG8_STAGE(PG8_SB(0, 0), cB, voffB); PG8_STAGE(PG8_SB(0, 1), cB + hstepB, voffB); PG8_STAGE(PG8_SA(0, 0), cA, voffA); PG8_STAGE(PG8_SA(0, 1), cA + hstepA, voffA);
;     if (wr == 1) PG8_BAR;
;     PG8_WAIT_V(2); PG8_BAR;
;     PG8_STAGE(PG8_SB(1, 0), cB + kstep, voffB); PG8_STAGE(PG8_SA(1, 0), cA + kstepA, voffA); PG8_STAGE(PG8_SB(1, 1), cB + hstepB + kstep, voffB);
;     PG8_WAIT_V(6); PG8_BAR;
.LBB0_446:
	s_lshl_b32 s46, s8, 6
	s_lshl_b32 s12, s8, 13
	s_mov_b64 s[8:9], 0x80
	s_and_b32 s1, s4, 3
	s_add_i32 m0, s42, 0x18000
	v_lshl_add_u64 v[6:7], v[6:7], 0, s[8:9]
	s_lshl_b32 s13, s4, 5
	s_lshl_b32 s14, s1, 12
	global_load_lds_dwordx4 v[6:7], off
	v_lshl_add_u64 v[4:5], v[4:5], 0, s[8:9]
	s_add_i32 m0, s42, 0x1a000
	s_add_i32 s47, s42, 0x8000
	s_add_i32 s48, s42, 0xa000
	global_load_lds_dwordx4 v[4:5], off
	v_lshl_add_u64 v[0:1], v[0:1], 0, s[8:9]
	s_mov_b32 m0, s47
	s_add_u32 s10, s30, 0x40080
	global_load_lds_dwordx4 v[0:1], off
	v_lshl_add_u64 v[0:1], v[2:3], 0, s[8:9]
	s_mov_b32 m0, s48
	s_addc_u32 s11, s31, 0
	global_load_lds_dwordx4 v[0:1], off
	s_add_i32 m0, s42, 0x1c000
	v_lshl_add_u64 v[0:1], s[10:11], 0, v[130:131]
	global_load_lds_dwordx4 v[0:1], off
	v_lshl_add_u64 v[0:1], s[10:11], 0, v[128:129]
	s_add_i32 m0, s42, 0x1e000
	v_and_b32_e32 v144, 15, v11
	global_load_lds_dwordx4 v[0:1], off
	s_waitcnt vmcnt(8)
	s_barrier
	v_lshrrev_b32_e32 v0, 1, v11
	v_and_b32_e32 v0, 24, v0
	v_lshlrev_b32_e32 v1, 1, v0
	v_lshlrev_b32_e32 v2, 2, v11
	s_cmpk_lt_u32 s3, 0x100
	v_lshl_or_b32 v1, v144, 6, v1
	v_and_b32_e32 v2, 32, v2
	s_cselect_b64 s[10:11], -1, 0
	s_and_b32 s3, s46, 0xc0
	v_bitop3_b32 v3, v1, s12, v2 bitop3:0xde
	v_bitop3_b32 v145, v1, s14, v2 bitop3:0xde
	v_or_b32_e32 v1, s3, v144
	v_lshlrev_b32_e32 v132, 7, v1
	v_lshlrev_b32_e32 v1, 14, v12
	v_and_b32_e32 v1, 0xffff8000, v1
	v_lshl_add_u32 v1, v13, 11, v1
	v_and_b32_e32 v2, 1, v12
	v_lshl_or_b32 v1, v2, 6, v1
	s_sext_i32_i16 s1, s2
	s_and_b32 s2, s13, 32
	v_readlane_b32 s12, v254, 9
	v_lshl_add_u32 v136, v14, 1, v1
	v_lshlrev_b32_e32 v1, 14, v8
	v_readlane_b32 s13, v254, 10
	v_and_b32_e32 v1, 0xffff8000, v1
	s_waitcnt vmcnt(6)
	v_readlane_b32 s12, v254, 51
	v_lshl_add_u32 v1, v9, 11, v1
	v_and_b32_e32 v2, 1, v8
	v_readlane_b32 s14, v254, 11
	v_readlane_b32 s13, v254, 52
	v_lshl_or_b32 v1, v2, 6, v1
	s_add_i32 s52, 0, 0x10000
	s_add_i32 s53, 0, 0x14000
	s_bfe_u32 s49, s4, 0x10001
	s_ashr_i32 s50, s14, 31
	s_mov_b32 s51, s14
	v_lshl_add_u64 v[134:135], s[12:13], 0, v[132:133]
	v_mov_b32_e32 v137, v133
	v_lshl_add_u32 v138, v10, 1, v1
	v_mov_b32_e32 v139, v133
	v_mov_b64_e32 v[140:141], 0xb00
	v_mov_b64_e32 v[142:143], 0xaff
	v_add_u32_e32 v146, s52, v145
	v_add_u32_e32 v147, s53, v145
	v_add_u32_e32 v148, 0, v3
	v_mov_b32_e32 v149, 0x358637bd
	s_mov_b32 s54, 0x800000
	s_lshl_b32 s4, s2, 1
	v_lshlrev_b32_e32 v132, 1, v0
	s_movk_i32 s55, 0x1000
	s_mov_b32 s56, s5
	s_barrier
	v_readlane_b32 s15, v254, 12
	s_branch .LBB0_449

; #define PG8_STAGE(bufoff, gbase, voff) do { _Pragma("unroll") for (int _i = 0; _i < 2; ++_i) \
;         __builtin_amdgcn_global_load_lds((const unsigned*)((const char*)(gbase) + (voff)[_i]), (LAS unsigned*)(lds + (bufoff) + ldsw + _i * 8192), 16, 0, 0); } while (0)
; #define PG8_WAIT_V(n) asm volatile("s_waitcnt vmcnt(" #n ")" ::: "memory")
; #define PG8_BAR __builtin_amdgcn_s_barrier()
; template <class Epi>
; __device__ __forceinline__ void gemm_phase(LAS unsigned char* lds, const Gemm g, const StaticOrder& S, const Epi& E) {
;     ...
;     const char* cA = (const char*)g.A + (size_t)cur.pm * tstepA; const char* cB = (const char*)g.Bt + (size_t)cur.pn * tstepB;
;     PG8_STAGE(PG8_SB(0, 0), cB, voffB); PG8_STAGE(PG8_SB(0, 1), cB + hstepB, voffB); PG8_STAGE(PG8_SA(0, 0), cA, voffA); PG8_STAGE(PG8_SA(0, 1), cA + hstepA, voffA);
;     if (wr == 1) PG8_BAR;
;     PG8_WAIT_V(2); PG8_BAR;
;     PG8_STAGE(PG8_SB(1, 0), cB + kstep, voffB); PG8_STAGE(PG8_SA(1, 0), cA + kstepA, voffA); PG8_STAGE(PG8_SB(1, 1), cB + hstepB + kstep, voffB);
;     PG8_WAIT_V(6); PG8_BAR;
.LBB0_534:
	s_mov_b64 s[38:39], 0x80
	s_and_b32 s5, s5, 3
	s_add_i32 m0, s46, 0x18000
	v_lshl_add_u64 v[2:3], v[2:3], 0, s[38:39]
	s_lshl_b32 s7, s6, 13
	s_lshl_b32 s10, s5, 12
	global_load_lds_dwordx4 v[2:3], off
	s_add_i32 m0, s46, 0x1a000
	s_add_u32 s8, s2, 0x8000
	v_lshl_add_u64 v[0:1], v[0:1], 0, s[38:39]
	s_addc_u32 s9, s3, 0
	s_add_i32 s51, s46, 0x8000
	global_load_lds_dwordx4 v[0:1], off
	v_lshl_add_u64 v[0:1], s[8:9], 0, v[192:193]
	s_mov_b32 m0, s51
	s_add_i32 s52, s46, 0xa000
	global_load_lds_dwordx4 v[0:1], off
	v_lshl_add_u64 v[0:1], s[8:9], 0, v[196:197]
	s_add_u32 s8, s0, 0xb0080
	s_mov_b32 m0, s52
	s_addc_u32 s9, s1, 0
	global_load_lds_dwordx4 v[0:1], off
	s_add_i32 m0, s46, 0x1c000
	v_lshl_add_u64 v[0:1], s[8:9], 0, v[194:195]
	global_load_lds_dwordx4 v[0:1], off
	v_lshl_add_u64 v[0:1], s[8:9], 0, v[198:199]
	s_add_i32 m0, s46, 0x1e000
	s_cmpk_lt_u32 s4, 0x100
	global_load_lds_dwordx4 v[0:1], off
	s_waitcnt vmcnt(8)
	s_barrier
	v_bfe_u32 v1, v4, 4, 2
	v_and_b32_e32 v0, 15, v4
	v_lshlrev_b32_e32 v3, 4, v1
	v_lshl_or_b32 v235, s6, 6, v0
	v_lshl_or_b32 v0, v0, 6, v3
	v_lshlrev_b32_e32 v3, 2, v4
	v_and_b32_e32 v3, 32, v3
	v_bitop3_b32 v4, v0, s7, v3 bitop3:0xde
	v_bitop3_b32 v236, v0, s10, v3 bitop3:0xde
	v_lshlrev_b32_e32 v0, 10, v5
	v_lshlrev_b32_e32 v2, 3, v1
	v_and_b32_e32 v0, 0xfffff800, v0
	v_lshl_or_b32 v237, s5, 6, v2
	v_cmp_eq_u32_e64 s[4:5], 0, v1
	v_lshl_add_u32 v0, v6, 7, v0
	v_and_b32_e32 v1, 1, v5
	v_readlane_b32 s8, v254, 9
	v_lshl_or_b32 v0, v1, 6, v0
	v_readlane_b32 s10, v254, 11
	v_readlane_b32 s6, v254, 0
	v_lshl_add_u32 v200, v7, 1, v0
	v_lshlrev_b32_e32 v0, 10, v8
	s_cselect_b64 s[40:41], -1, 0
	s_ashr_i32 s54, s10, 31
	s_ashr_i32 s56, s6, 31
	v_and_b32_e32 v0, 0xfffff800, v0
	s_waitcnt vmcnt(6)
	v_readlane_b32 s9, v254, 10
	s_add_u32 s57, s8, 0x8b00000
	v_lshl_add_u32 v0, v9, 7, v0
	v_and_b32_e32 v1, 1, v8
	s_addc_u32 s58, s9, 0
	v_lshl_or_b32 v0, v1, 6, v0
	s_add_i32 s59, 0, 0x10000
	s_add_i32 s60, 0, 0x14000
	s_mov_b32 s53, 0x8000
	s_mov_b32 s55, s10
	v_mov_b32_e32 v201, v195
	v_lshl_add_u32 v202, v10, 1, v0
	v_mov_b32_e32 v203, v195
	v_mov_b64_e32 v[204:205], 0x200
	v_mov_b64_e32 v[206:207], 0x1ff
	v_add_u32_e32 v238, s59, v236
	v_add_u32_e32 v239, s60, v236
	v_add_u32_e32 v240, 0, v4
	s_mov_b32 s61, 0x8020
	v_mbcnt_hi_u32_b32 v241, -1, v234
	s_barrier
	v_readlane_b32 s11, v254, 12
	s_branch .LBB0_537

; #define PG8_STAGE(bufoff, gbase, voff) do { _Pragma("unroll") for (int _i = 0; _i < 2; ++_i) \
;         __builtin_amdgcn_global_load_lds((const unsigned*)((const char*)(gbase) + (voff)[_i]), (LAS unsigned*)(lds + (bufoff) + ldsw + _i * 8192), 16, 0, 0); } while (0)
; #define PG8_WAIT_V(n) asm volatile("s_waitcnt vmcnt(" #n ")" ::: "memory")
; #define PG8_BAR __builtin_amdgcn_s_barrier()
; template <class Epi>
; __device__ __forceinline__ void gemm_phase(LAS unsigned char* lds, const Gemm g, const StaticOrder& S, const Epi& E) {
;     ...
;     const char* cA = (const char*)g.A + (size_t)cur.pm * tstepA; const char* cB = (const char*)g.Bt + (size_t)cur.pn * tstepB;
;     PG8_STAGE(PG8_SB(0, 0), cB, voffB); PG8_STAGE(PG8_SB(0, 1), cB + hstepB, voffB); PG8_STAGE(PG8_SA(0, 0), cA, voffA); PG8_STAGE(PG8_SA(0, 1), cA + hstepA, voffA);
;     if (wr == 1) PG8_BAR;
;     PG8_WAIT_V(2); PG8_BAR;
;     PG8_STAGE(PG8_SB(1, 0), cB + kstep, voffB); PG8_STAGE(PG8_SA(1, 0), cA + kstepA, voffA); PG8_STAGE(PG8_SB(1, 1), cB + hstepB + kstep, voffB);
;     PG8_WAIT_V(6); PG8_BAR;
.LBB0_681:
	s_mov_b64 s[38:39], 0x80
	s_and_b32 s60, s4, 3
	s_add_i32 m0, s56, 0x18000
	v_lshl_add_u64 v[6:7], v[6:7], 0, s[38:39]
	s_lshl_b32 s61, s5, 6
	s_lshl_b32 s1, s5, 13
	s_lshl_b32 s3, s60, 12
	global_load_lds_dwordx4 v[6:7], off
	v_lshl_add_u64 v[4:5], v[4:5], 0, s[38:39]
	s_add_i32 m0, s56, 0x1a000
	s_add_i32 s62, s56, 0x8000
	s_add_i32 s63, s56, 0xa000
	global_load_lds_dwordx4 v[4:5], off
	v_lshl_add_u64 v[0:1], v[0:1], 0, s[38:39]
	s_mov_b32 m0, s62
	s_add_u32 s4, s12, 0x40080
	global_load_lds_dwordx4 v[0:1], off
	v_lshl_add_u64 v[0:1], v[2:3], 0, s[38:39]
	s_mov_b32 m0, s63
	s_addc_u32 s5, s13, 0
	global_load_lds_dwordx4 v[0:1], off
	s_add_i32 m0, s56, 0x1c000
	v_lshl_add_u64 v[0:1], s[4:5], 0, v[138:139]
	global_load_lds_dwordx4 v[0:1], off
	v_lshl_add_u64 v[0:1], s[4:5], 0, v[140:141]
	s_add_i32 m0, s56, 0x1e000
	v_and_b32_e32 v145, 15, v8
	global_load_lds_dwordx4 v[0:1], off
	s_waitcnt vmcnt(8)
	s_barrier
	v_bfe_u32 v0, v8, 4, 2
	v_lshlrev_b32_e32 v144, 3, v0
	v_lshlrev_b32_e32 v1, 4, v0
	v_lshlrev_b32_e32 v2, 2, v8
	s_cmpk_lt_u32 s6, 0x100
	v_cmp_eq_u32_e64 s[4:5], 0, v0
	v_cmp_gt_u32_e64 s[6:7], 2, v0
	v_lshlrev_b32_e32 v0, 14, v9
	v_lshl_or_b32 v1, v145, 6, v1
	v_and_b32_e32 v2, 32, v2
	v_and_b32_e32 v0, 0xffff8000, v0
	v_bitop3_b32 v3, v1, s1, v2 bitop3:0xde
	v_bitop3_b32 v157, v1, s3, v2 bitop3:0xde
	v_lshl_add_u32 v0, v10, 11, v0
	v_and_b32_e32 v1, 1, v9
	v_lshl_or_b32 v0, v1, 6, v0
	v_lshl_add_u32 v146, v11, 1, v0
	v_lshlrev_b32_e32 v0, 14, v12
	v_and_b32_e32 v0, 0xffff8000, v0
	s_waitcnt vmcnt(6)
	v_readlane_b32 s16, v254, 9
	v_lshl_add_u32 v0, v13, 11, v0
	v_and_b32_e32 v1, 1, v12
	s_cselect_b64 s[40:41], -1, 0
	s_lshl_b32 s1, s60, 6
	v_readlane_b32 s18, v254, 11
	v_readlane_b32 s3, v254, 0
	v_lshl_or_b32 v0, v1, 6, v0
	s_add_i32 s72, 0, 0x10000
	s_add_i32 s73, 0, 0x14000
	s_mov_b32 s64, 0x8000
	v_or_b32_e32 v170, s1, v144
	s_ashr_i32 s65, s18, 31
	s_mov_b32 s66, s18
	s_ashr_i32 s67, s3, 31
	v_mov_b32_e32 v147, v143
	v_lshl_add_u32 v148, v14, 1, v0
	v_mov_b32_e32 v149, v143
	v_mov_b64_e32 v[150:151], 0x1900
	v_mov_b64_e32 v[152:153], 0x18ff
	v_add_u32_e32 v171, s72, v157
	v_add_u32_e32 v172, s73, v157
	v_add_u32_e32 v173, 0, v3
	v_mov_b32_e32 v174, 0x358637bd
	s_mov_b32 s74, 0x800000
	s_movk_i32 s75, 0x7fff
	s_mov_b32 s42, 0x3e000000
	s_lshl_b32 s44, s1, 1
	s_movk_i32 s89, 0x6400
	v_lshlrev_b32_e32 v154, 1, v144
	s_movk_i32 s90, 0x3000
	s_movk_i32 s91, 0x7df
	s_movk_i32 s92, 0x7ef
	s_mov_b32 s93, 0x8020
	s_movk_i32 s96, 0x7ff
	v_mov_b32_e32 v175, 0x3d800000
	v_mov_b32_e32 v176, 0x7cf
	v_mov_b32_e32 v177, 0x800
	v_mbcnt_hi_u32_b32 v178, -1, v234
	s_mov_b32 s97, 0
	s_barrier
	v_readlane_b32 s17, v254, 10
	v_readlane_b32 s19, v254, 12
	s_branch .LBB0_684

; #define PG8_STAGE(bufoff, gbase, voff) do { _Pragma("unroll") for (int _i = 0; _i < 2; ++_i) \
;         __builtin_amdgcn_global_load_lds((const unsigned*)((const char*)(gbase) + (voff)[_i]), (LAS unsigned*)(lds + (bufoff) + ldsw + _i * 8192), 16, 0, 0); } while (0)
; #define PG8_WAIT_V(n) asm volatile("s_waitcnt vmcnt(" #n ")" ::: "memory")
; #define PG8_BAR __builtin_amdgcn_s_barrier()
; template <class Epi>
; __device__ __forceinline__ void gemm_phase(LAS unsigned char* lds, const Gemm g, const StaticOrder& S, const Epi& E) {
;     ...
;     const char* cA = (const char*)g.A + (size_t)cur.pm * tstepA; const char* cB = (const char*)g.Bt + (size_t)cur.pn * tstepB;
;     PG8_STAGE(PG8_SB(0, 0), cB, voffB); PG8_STAGE(PG8_SB(0, 1), cB + hstepB, voffB); PG8_STAGE(PG8_SA(0, 0), cA, voffA); PG8_STAGE(PG8_SA(0, 1), cA + hstepA, voffA);
;     if (wr == 1) PG8_BAR;
;     PG8_WAIT_V(2); PG8_BAR;
;     PG8_STAGE(PG8_SB(1, 0), cB + kstep, voffB); PG8_STAGE(PG8_SA(1, 0), cA + kstepA, voffA); PG8_STAGE(PG8_SB(1, 1), cB + hstepB + kstep, voffB);
;     PG8_WAIT_V(6); PG8_BAR;
.LBB0_1448:
	s_and_b32 s10, s2, 3
	s_mov_b64 s[2:3], 0x80
	s_add_i32 m0, s26, 0x18000
	v_lshl_add_u64 v[6:7], v[6:7], 0, s[2:3]
	s_lshl_b32 s11, s7, 13
	s_lshl_b32 s12, s10, 12
	global_load_lds_dwordx4 v[6:7], off
	v_lshl_add_u64 v[4:5], v[4:5], 0, s[2:3]
	s_add_i32 m0, s26, 0x1a000
	s_add_i32 s31, s26, 0x8000
	s_add_i32 s33, s26, 0xa000
	global_load_lds_dwordx4 v[4:5], off
	v_lshl_add_u64 v[0:1], v[0:1], 0, s[2:3]
	s_mov_b32 m0, s31
	s_add_u32 s8, s20, 0x20080
	global_load_lds_dwordx4 v[0:1], off
	v_lshl_add_u64 v[0:1], v[2:3], 0, s[2:3]
	s_mov_b32 m0, s33
	s_addc_u32 s9, s21, 0
	global_load_lds_dwordx4 v[0:1], off
	s_add_i32 m0, s26, 0x1c000
	v_lshl_add_u64 v[0:1], s[8:9], 0, v[170:171]
	global_load_lds_dwordx4 v[0:1], off
	v_lshl_add_u64 v[0:1], s[8:9], 0, v[174:175]
	s_add_i32 m0, s26, 0x1e000
	s_sext_i32_i8 s41, s4
	global_load_lds_dwordx4 v[0:1], off
	s_waitcnt vmcnt(8)
	s_barrier
	v_lshrrev_b32_e32 v1, 1, v8
	v_and_b32_e32 v1, 24, v1
	v_and_b32_e32 v0, 15, v8
	v_lshlrev_b32_e32 v2, 1, v1
	v_lshl_or_b32 v196, s7, 6, v0
	v_lshl_or_b32 v0, v0, 6, v2
	v_lshlrev_b32_e32 v2, 2, v8
	v_and_b32_e32 v2, 32, v2
	v_bitop3_b32 v3, v0, s11, v2 bitop3:0xde
	v_bitop3_b32 v197, v0, s12, v2 bitop3:0xde
	v_lshl_or_b32 v198, s10, 6, v1
	v_lshrrev_b32_e32 v1, 1, v9
	v_mul_lo_u32 v0, v11, s6
	s_mov_b32 s7, 0x32000
	s_cmpk_lt_u32 s5, 0x100
	v_mad_u64_u32 v[0:1], s[4:5], v1, s7, v[0:1]
	v_or_b32_e32 v0, v0, v10
	v_add_lshl_u32 v0, v0, v12, 1
	v_mov_b32_e32 v1, v171
	s_mov_b64 s[4:5], 0x320080
	v_lshl_add_u64 v[176:177], v[0:1], 0, s[4:5]
	v_lshrrev_b32_e32 v1, 1, v13
	v_mul_lo_u32 v0, v14, s6
	v_mad_u64_u32 v[0:1], s[6:7], v1, s7, v[0:1]
	s_waitcnt vmcnt(6)
	v_readlane_b32 s12, v254, 9
	v_or_b32_e32 v0, v0, v15
	s_cselect_b64 s[8:9], -1, 0
	v_readlane_b32 s14, v254, 11
	v_add_lshl_u32 v0, v0, v16, 1
	v_mov_b32_e32 v1, v171
	s_add_i32 s36, 0, 0x10000
	s_add_i32 s37, 0, 0x14000
	s_ashr_i32 s34, s14, 31
	s_mov_b32 s35, s14
	v_lshl_add_u64 v[178:179], v[0:1], 0, s[4:5]
	v_mov_b64_e32 v[180:181], 0x200
	v_mov_b64_e32 v[182:183], 0x1ff
	v_add_u32_e32 v199, s36, v197
	v_add_u32_e32 v200, s37, v197
	v_add_u32_e32 v201, 0, v3
	s_movk_i32 s38, 0x6400
	s_mov_b64 s[10:11], 0x5400
	s_barrier
	v_readlane_b32 s13, v254, 10
	v_readlane_b32 s15, v254, 12
	s_branch .LBB0_1451

; #define PG8_STAGE(bufoff, gbase, voff) do { _Pragma("unroll") for (int _i = 0; _i < 2; ++_i) \
;         __builtin_amdgcn_global_load_lds((const unsigned*)((const char*)(gbase) + (voff)[_i]), (LAS unsigned*)(lds + (bufoff) + ldsw + _i * 8192), 16, 0, 0); } while (0)
; #define PG8_WAIT_V(n) asm volatile("s_waitcnt vmcnt(" #n ")" ::: "memory")
; #define PG8_BAR __builtin_amdgcn_s_barrier()
; template <class Epi>
; __device__ __forceinline__ void gemm_phase(LAS unsigned char* lds, const Gemm g, const StaticOrder& S, const Epi& E) {
;     ...
;     const char* cA = (const char*)g.A + (size_t)cur.pm * tstepA; const char* cB = (const char*)g.Bt + (size_t)cur.pn * tstepB;
;     PG8_STAGE(PG8_SB(0, 0), cB, voffB); PG8_STAGE(PG8_SB(0, 1), cB + hstepB, voffB); PG8_STAGE(PG8_SA(0, 0), cA, voffA); PG8_STAGE(PG8_SA(0, 1), cA + hstepA, voffA);
;     if (wr == 1) PG8_BAR;
;     PG8_WAIT_V(2); PG8_BAR;
;     PG8_STAGE(PG8_SB(1, 0), cB + kstep, voffB); PG8_STAGE(PG8_SA(1, 0), cA + kstepA, voffA); PG8_STAGE(PG8_SB(1, 1), cB + hstepB + kstep, voffB);
;     PG8_WAIT_V(6); PG8_BAR;
.LBB0_1491:
	s_and_b32 s12, s2, 3
	s_mov_b64 s[2:3], 0x80
	s_add_i32 m0, s30, 0x18000
	v_lshl_add_u64 v[6:7], v[6:7], 0, s[2:3]
	s_lshl_b32 s13, s9, 13
	s_lshl_b32 s14, s12, 12
	global_load_lds_dwordx4 v[6:7], off
	v_lshl_add_u64 v[4:5], v[4:5], 0, s[2:3]
	s_add_i32 m0, s30, 0x1a000
	s_add_i32 s36, s30, 0x8000
	s_add_i32 s37, s30, 0xa000
	global_load_lds_dwordx4 v[4:5], off
	v_lshl_add_u64 v[0:1], v[0:1], 0, s[2:3]
	s_mov_b32 m0, s36
	s_add_u32 s10, s22, 0x80080
	global_load_lds_dwordx4 v[0:1], off
	v_lshl_add_u64 v[0:1], v[2:3], 0, s[2:3]
	s_mov_b32 m0, s37
	s_addc_u32 s11, s23, 0
	global_load_lds_dwordx4 v[0:1], off
	s_add_i32 m0, s30, 0x1c000
	v_lshl_add_u64 v[0:1], s[10:11], 0, v[130:131]
	global_load_lds_dwordx4 v[0:1], off
	v_lshl_add_u64 v[0:1], s[10:11], 0, v[134:135]
	s_add_i32 m0, s30, 0x1e000
	s_sext_i32_i8 s46, s6
	global_load_lds_dwordx4 v[0:1], off
	s_waitcnt vmcnt(8)
	s_barrier
	v_lshrrev_b32_e32 v1, 1, v8
	v_and_b32_e32 v1, 24, v1
	v_and_b32_e32 v0, 15, v8
	v_lshlrev_b32_e32 v2, 1, v1
	v_lshl_or_b32 v152, s9, 6, v0
	v_lshl_or_b32 v0, v0, 6, v2
	v_lshlrev_b32_e32 v2, 2, v8
	v_and_b32_e32 v2, 32, v2
	v_bitop3_b32 v3, v0, s13, v2 bitop3:0xde
	v_bitop3_b32 v153, v0, s14, v2 bitop3:0xde
	v_lshl_or_b32 v154, s12, 6, v1
	v_lshrrev_b32_e32 v1, 1, v9
	v_mul_lo_u32 v0, v11, s8
	s_mov_b32 s9, 0x32000
	s_cmpk_lt_u32 s7, 0x100
	v_mad_u64_u32 v[0:1], s[6:7], v1, s9, v[0:1]
	v_or_b32_e32 v0, v0, v10
	v_add_lshl_u32 v0, v0, v12, 1
	v_mov_b32_e32 v1, v131
	s_mov_b64 s[6:7], 0x320080
	v_lshl_add_u64 v[136:137], v[0:1], 0, s[6:7]
	v_lshrrev_b32_e32 v1, 1, v13
	v_mul_lo_u32 v0, v14, s8
	v_mad_u64_u32 v[0:1], s[8:9], v1, s9, v[0:1]
	s_waitcnt vmcnt(6)
	v_readlane_b32 s16, v254, 9
	v_or_b32_e32 v0, v0, v15
	s_cselect_b64 s[10:11], -1, 0
	v_readlane_b32 s18, v254, 11
	v_add_lshl_u32 v0, v0, v16, 1
	v_mov_b32_e32 v1, v131
	s_add_i32 s40, 0, 0x10000
	s_add_i32 s41, 0, 0x14000
	s_ashr_i32 s38, s18, 31
	s_mov_b32 s39, s18
	v_lshl_add_u64 v[138:139], v[0:1], 0, s[6:7]
	v_mov_b64_e32 v[140:141], 0x200
	v_mov_b64_e32 v[142:143], 0x1ff
	v_add_u32_e32 v155, s40, v153
	v_add_u32_e32 v156, s41, v153
	v_add_u32_e32 v157, 0, v3
	s_movk_i32 s42, 0x6400
	s_mov_b64 s[12:13], 0x5c00
	s_movk_i32 s43, 0x5000
	s_barrier
	v_readlane_b32 s17, v254, 10
	v_readlane_b32 s19, v254, 12
	s_branch .LBB0_1494

; #define PG8_STAGE(bufoff, gbase, voff) do { _Pragma("unroll") for (int _i = 0; _i < 2; ++_i) \
;         __builtin_amdgcn_global_load_lds((const unsigned*)((const char*)(gbase) + (voff)[_i]), (LAS unsigned*)(lds + (bufoff) + ldsw + _i * 8192), 16, 0, 0); } while (0)
; #define PG8_WAIT_V(n) asm volatile("s_waitcnt vmcnt(" #n ")" ::: "memory")
; #define PG8_BAR __builtin_amdgcn_s_barrier()
; template <class Epi>
; __device__ __forceinline__ void gemm_phase(LAS unsigned char* lds, const Gemm g, const StaticOrder& S, const Epi& E) {
;     ...
;     const char* cA = (const char*)g.A + (size_t)cur.pm * tstepA; const char* cB = (const char*)g.Bt + (size_t)cur.pn * tstepB;
;     PG8_STAGE(PG8_SB(0, 0), cB, voffB); PG8_STAGE(PG8_SB(0, 1), cB + hstepB, voffB); PG8_STAGE(PG8_SA(0, 0), cA, voffA); PG8_STAGE(PG8_SA(0, 1), cA + hstepA, voffA);
;     if (wr == 1) PG8_BAR;
;     PG8_WAIT_V(2); PG8_BAR;
;     PG8_STAGE(PG8_SB(1, 0), cB + kstep, voffB); PG8_STAGE(PG8_SA(1, 0), cA + kstepA, voffA); PG8_STAGE(PG8_SB(1, 1), cB + hstepB + kstep, voffB);
;     PG8_WAIT_V(6); PG8_BAR;
.LBB0_1588:
	s_mov_b64 s[22:23], 0x80
	s_and_b32 s1, s7, 3
	s_add_i32 m0, s3, 0x18000
	v_lshl_add_u64 v[6:7], v[6:7], 0, s[22:23]
	s_lshl_b32 s7, s8, 13
	s_lshl_b32 s9, s1, 12
	global_load_lds_dwordx4 v[6:7], off
	v_lshl_add_u64 v[4:5], v[4:5], 0, s[22:23]
	s_add_i32 m0, s3, 0x1a000
	s_add_i32 s40, s3, 0x8000
	s_add_i32 s41, s3, 0xa000
	global_load_lds_dwordx4 v[4:5], off
	v_lshl_add_u64 v[2:3], v[2:3], 0, s[22:23]
	s_mov_b32 m0, s40
	s_add_u32 s14, s12, 0x40080
	global_load_lds_dwordx4 v[2:3], off
	v_lshl_add_u64 v[0:1], v[0:1], 0, s[22:23]
	s_mov_b32 m0, s41
	s_addc_u32 s15, s13, 0
	global_load_lds_dwordx4 v[0:1], off
	s_add_i32 m0, s3, 0x1c000
	v_lshl_add_u64 v[0:1], s[14:15], 0, v[192:193]
	global_load_lds_dwordx4 v[0:1], off
	v_lshl_add_u64 v[0:1], s[14:15], 0, v[194:195]
	s_add_i32 m0, s3, 0x1e000
	s_cmpk_lt_u32 s6, 0x100
	global_load_lds_dwordx4 v[0:1], off
	s_waitcnt vmcnt(8)
	s_barrier
	v_bfe_u32 v1, v8, 4, 2
	v_and_b32_e32 v0, 15, v8
	v_lshlrev_b32_e32 v3, 4, v1
	v_lshl_or_b32 v209, s8, 6, v0
	v_lshl_or_b32 v0, v0, 6, v3
	v_lshlrev_b32_e32 v3, 2, v8
	v_and_b32_e32 v3, 32, v3
	v_bitop3_b32 v4, v0, s7, v3 bitop3:0xde
	v_bitop3_b32 v228, v0, s9, v3 bitop3:0xde
	v_lshlrev_b32_e32 v0, 14, v9
	v_and_b32_e32 v0, 0xffff8000, v0
	v_lshlrev_b32_e32 v2, 3, v1
	v_cmp_eq_u32_e64 s[6:7], 0, v1
	v_lshl_add_u32 v0, v10, 11, v0
	v_and_b32_e32 v1, 1, v9
	v_readlane_b32 s28, v254, 9
	v_lshl_or_b32 v0, v1, 6, v0
	v_lshl_or_b32 v229, s1, 6, v2
	v_readlane_b32 s30, v254, 11
	v_readlane_b32 s1, v254, 0
	v_lshl_add_u32 v196, v11, 1, v0
	v_lshlrev_b32_e32 v0, 14, v12
	s_cselect_b64 s[24:25], -1, 0
	s_ashr_i32 s43, s30, 31
	s_ashr_i32 s45, s1, 31
	v_and_b32_e32 v0, 0xffff8000, v0
	s_waitcnt vmcnt(6)
	v_readlane_b32 s29, v254, 10
	s_add_u32 s46, s28, 0x8b00000
	v_lshl_add_u32 v0, v13, 11, v0
	v_and_b32_e32 v1, 1, v12
	s_addc_u32 s47, s29, 0
	v_lshl_or_b32 v0, v1, 6, v0
	s_add_i32 s48, 0, 0x10000
	s_add_i32 s49, 0, 0x14000
	s_mov_b32 s42, 0x8000
	s_mov_b32 s44, s30
	v_mov_b32_e32 v197, v193
	v_lshl_add_u32 v198, v14, 1, v0
	v_mov_b32_e32 v199, v193
	v_mov_b64_e32 v[200:201], 0x200
	v_mov_b64_e32 v[202:203], 0x1ff
	v_add_u32_e32 v230, s48, v228
	v_add_u32_e32 v231, s49, v228
	v_add_u32_e32 v232, 0, v4
	s_mov_b32 s50, 0x8020
	v_mbcnt_hi_u32_b32 v233, -1, v234
	s_barrier
	v_readlane_b32 s31, v254, 12
	s_branch .LBB0_1591

; #define PG8_STAGE(bufoff, gbase, voff) do { _Pragma("unroll") for (int _i = 0; _i < 2; ++_i) \
;         __builtin_amdgcn_global_load_lds((const unsigned*)((const char*)(gbase) + (voff)[_i]), (LAS unsigned*)(lds + (bufoff) + ldsw + _i * 8192), 16, 0, 0); } while (0)
; #define PG8_WAIT_V(n) asm volatile("s_waitcnt vmcnt(" #n ")" ::: "memory")
; #define PG8_BAR __builtin_amdgcn_s_barrier()
; template <class Epi>
; __device__ __forceinline__ void gemm_phase(LAS unsigned char* lds, const Gemm g, const StaticOrder& S, const Epi& E) {
;     ...
;     const char* cA = (const char*)g.A + (size_t)cur.pm * tstepA; const char* cB = (const char*)g.Bt + (size_t)cur.pn * tstepB;
;     PG8_STAGE(PG8_SB(0, 0), cB, voffB); PG8_STAGE(PG8_SB(0, 1), cB + hstepB, voffB); PG8_STAGE(PG8_SA(0, 0), cA, voffA); PG8_STAGE(PG8_SA(0, 1), cA + hstepA, voffA);
;     if (wr == 1) PG8_BAR;
;     PG8_WAIT_V(2); PG8_BAR;
;     PG8_STAGE(PG8_SB(1, 0), cB + kstep, voffB); PG8_STAGE(PG8_SA(1, 0), cA + kstepA, voffA); PG8_STAGE(PG8_SB(1, 1), cB + hstepB + kstep, voffB);
;     PG8_WAIT_V(6); PG8_BAR;
.LBB0_1726:
	s_lshl_b32 s40, s10, 6
	s_lshl_b32 s14, s10, 13
	s_mov_b64 s[10:11], 0x80
	s_and_b32 s1, s7, 3
	s_add_i32 m0, s36, 0x18000
	v_lshl_add_u64 v[6:7], v[6:7], 0, s[10:11]
	s_lshl_b32 s15, s7, 5
	s_lshl_b32 s20, s1, 12
	global_load_lds_dwordx4 v[6:7], off
	v_lshl_add_u64 v[4:5], v[4:5], 0, s[10:11]
	s_add_i32 m0, s36, 0x1a000
	s_add_i32 s41, s36, 0x8000
	s_add_i32 s42, s36, 0xa000
	global_load_lds_dwordx4 v[4:5], off
	v_lshl_add_u64 v[0:1], v[0:1], 0, s[10:11]
	s_mov_b32 m0, s41
	s_add_u32 s12, s28, 0x40080
	global_load_lds_dwordx4 v[0:1], off
	v_lshl_add_u64 v[0:1], v[2:3], 0, s[10:11]
	s_mov_b32 m0, s42
	s_addc_u32 s13, s29, 0
	global_load_lds_dwordx4 v[0:1], off
	s_add_i32 m0, s36, 0x1c000
	v_lshl_add_u64 v[0:1], s[12:13], 0, v[130:131]
	global_load_lds_dwordx4 v[0:1], off
	v_lshl_add_u64 v[0:1], s[12:13], 0, v[128:129]
	s_add_i32 m0, s36, 0x1e000
	v_and_b32_e32 v144, 15, v11
	global_load_lds_dwordx4 v[0:1], off
	s_waitcnt vmcnt(8)
	s_barrier
	v_lshrrev_b32_e32 v0, 1, v11
	v_and_b32_e32 v0, 24, v0
	v_lshlrev_b32_e32 v1, 1, v0
	v_lshlrev_b32_e32 v2, 2, v11
	s_cmpk_lt_u32 s6, 0x100
	v_lshl_or_b32 v1, v144, 6, v1
	v_and_b32_e32 v2, 32, v2
	s_cselect_b64 s[12:13], -1, 0
	s_and_b32 s6, s40, 0xc0
	v_bitop3_b32 v3, v1, s14, v2 bitop3:0xde
	v_bitop3_b32 v145, v1, s20, v2 bitop3:0xde
	v_or_b32_e32 v1, s6, v144
	v_lshlrev_b32_e32 v132, 7, v1
	v_lshlrev_b32_e32 v1, 14, v12
	v_and_b32_e32 v1, 0xffff8000, v1
	v_lshl_add_u32 v1, v13, 11, v1
	v_and_b32_e32 v2, 1, v12
	v_lshl_or_b32 v1, v2, 6, v1
	v_lshl_add_u32 v136, v14, 1, v1
	v_lshlrev_b32_e32 v1, 14, v8
	v_and_b32_e32 v1, 0xffff8000, v1
	s_waitcnt vmcnt(6)
	s_bfe_u32 s43, s7, 0x10001
	v_readlane_b32 s20, v254, 9
	v_readlane_b32 s6, v254, 51
	v_lshl_add_u32 v1, v9, 11, v1
	v_and_b32_e32 v2, 1, v8
	s_sext_i32_i16 s1, s2
	s_and_b32 s2, s15, 32
	v_readlane_b32 s22, v254, 11
	v_readlane_b32 s7, v254, 52
	v_lshl_or_b32 v1, v2, 6, v1
	s_add_i32 s46, 0, 0x10000
	s_add_i32 s47, 0, 0x14000
	s_ashr_i32 s44, s22, 31
	s_mov_b32 s45, s22
	v_lshl_add_u64 v[134:135], s[6:7], 0, v[132:133]
	v_mov_b32_e32 v137, v133
	v_lshl_add_u32 v138, v10, 1, v1
	v_mov_b32_e32 v139, v133
	v_mov_b64_e32 v[140:141], 0xb00
	v_mov_b64_e32 v[142:143], 0xaff
	v_add_u32_e32 v146, s46, v145
	v_add_u32_e32 v147, s47, v145
	v_add_u32_e32 v148, 0, v3
	v_mov_b32_e32 v149, 0x358637bd
	s_mov_b32 s48, 0x800000
	s_lshl_b32 s2, s2, 1
	v_lshlrev_b32_e32 v132, 1, v0
	s_movk_i32 s49, 0x1000
	s_mov_b32 s50, s3
	s_barrier
	v_readlane_b32 s21, v254, 10
	v_readlane_b32 s23, v254, 12
	s_branch .LBB0_1729

; #define PG8_STAGE(bufoff, gbase, voff) do { _Pragma("unroll") for (int _i = 0; _i < 2; ++_i) \
;         __builtin_amdgcn_global_load_lds((const unsigned*)((const char*)(gbase) + (voff)[_i]), (LAS unsigned*)(lds + (bufoff) + ldsw + _i * 8192), 16, 0, 0); } while (0)
; #define PG8_WAIT_V(n) asm volatile("s_waitcnt vmcnt(" #n ")" ::: "memory")
; #define PG8_BAR __builtin_amdgcn_s_barrier()
; template <class Epi>
; __device__ __forceinline__ void gemm_phase(LAS unsigned char* lds, const Gemm g, const StaticOrder& S, const Epi& E) {
;     ...
;     const char* cA = (const char*)g.A + (size_t)cur.pm * tstepA; const char* cB = (const char*)g.Bt + (size_t)cur.pn * tstepB;
;     PG8_STAGE(PG8_SB(0, 0), cB, voffB); PG8_STAGE(PG8_SB(0, 1), cB + hstepB, voffB); PG8_STAGE(PG8_SA(0, 0), cA, voffA); PG8_STAGE(PG8_SA(0, 1), cA + hstepA, voffA);
;     if (wr == 1) PG8_BAR;
;     PG8_WAIT_V(2); PG8_BAR;
;     PG8_STAGE(PG8_SB(1, 0), cB + kstep, voffB); PG8_STAGE(PG8_SA(1, 0), cA + kstepA, voffA); PG8_STAGE(PG8_SB(1, 1), cB + hstepB + kstep, voffB);
;     PG8_WAIT_V(6); PG8_BAR;
.LBB0_1814:
	s_mov_b64 s[20:21], 0x80
	s_and_b32 s0, s0, 3
	s_add_i32 m0, s31, 0x18000
	v_lshl_add_u64 v[2:3], v[2:3], 0, s[20:21]
	s_lshl_b32 s3, s1, 13
	s_lshl_b32 s14, s0, 12
	global_load_lds_dwordx4 v[2:3], off
	s_add_i32 m0, s31, 0x1a000
	s_add_u32 s10, s8, 0x8000
	v_lshl_add_u64 v[0:1], v[0:1], 0, s[20:21]
	s_addc_u32 s11, s9, 0
	s_add_i32 s37, s31, 0x8000
	global_load_lds_dwordx4 v[0:1], off
	v_lshl_add_u64 v[0:1], s[10:11], 0, v[192:193]
	s_mov_b32 m0, s37
	s_add_i32 s38, s31, 0xa000
	global_load_lds_dwordx4 v[0:1], off
	v_lshl_add_u64 v[0:1], s[10:11], 0, v[196:197]
	s_add_u32 s10, s6, 0xb0080
	s_mov_b32 m0, s38
	s_addc_u32 s11, s7, 0
	global_load_lds_dwordx4 v[0:1], off
	s_add_i32 m0, s31, 0x1c000
	v_lshl_add_u64 v[0:1], s[10:11], 0, v[194:195]
	global_load_lds_dwordx4 v[0:1], off
	v_lshl_add_u64 v[0:1], s[10:11], 0, v[198:199]
	s_add_i32 m0, s31, 0x1e000
	v_readlane_b32 s24, v254, 9
	global_load_lds_dwordx4 v[0:1], off
	s_waitcnt vmcnt(8)
	s_barrier
	v_lshrrev_b32_e32 v1, 1, v4
	v_and_b32_e32 v1, 24, v1
	v_and_b32_e32 v0, 15, v4
	v_lshlrev_b32_e32 v2, 1, v1
	v_lshl_or_b32 v209, s1, 6, v0
	v_lshl_or_b32 v0, v0, 6, v2
	v_lshlrev_b32_e32 v2, 2, v4
	v_and_b32_e32 v2, 32, v2
	v_bitop3_b32 v3, v0, s3, v2 bitop3:0xde
	v_bitop3_b32 v224, v0, s14, v2 bitop3:0xde
	v_lshlrev_b32_e32 v0, 10, v5
	v_and_b32_e32 v0, 0xfffff800, v0
	v_lshl_or_b32 v225, s0, 6, v1
	v_lshl_add_u32 v0, v6, 7, v0
	v_and_b32_e32 v1, 1, v5
	v_lshl_or_b32 v0, v1, 6, v0
	s_cmpk_lt_u32 s2, 0x100
	v_readlane_b32 s26, v254, 11
	v_readlane_b32 s1, v254, 0
	v_lshl_add_u32 v202, v7, 1, v0
	v_lshlrev_b32_e32 v0, 10, v8
	s_cselect_b64 s[22:23], -1, 0
	s_ashr_i32 s40, s26, 31
	s_ashr_i32 s41, s1, 31
	v_and_b32_e32 v0, 0xfffff800, v0
	s_waitcnt vmcnt(6)
	v_readlane_b32 s25, v254, 10
	s_add_u32 s42, s24, 0x8b00000
	v_lshl_add_u32 v0, v9, 7, v0
	v_and_b32_e32 v1, 1, v8
	s_addc_u32 s43, s25, 0
	v_lshl_or_b32 v0, v1, 6, v0
	s_add_i32 s44, 0, 0x10000
	s_add_i32 s45, 0, 0x14000
	s_mov_b32 s39, 0x8000
	v_mov_b32_e32 v203, v201
	v_lshl_add_u32 v204, v10, 1, v0
	v_mov_b32_e32 v205, v201
	v_mov_b64_e32 v[206:207], 0x200
	v_mov_b64_e32 v[210:211], 0x1ff
	v_add_u32_e32 v226, s44, v224
	v_add_u32_e32 v227, s45, v224
	v_add_u32_e32 v228, 0, v3
	s_mov_b32 s46, 0x8020
	v_bfrev_b32_e32 v229, 16
	s_barrier
	v_readlane_b32 s27, v254, 12
	s_branch .LBB0_1817
